# grid barrier moved from after job 6 (down-proj) to after job 7 (ple proj) so job 7 fills job 6 tail skew
# speedup vs baseline: 1.0083x; 1.0083x over previous
.LBB0_583:
	v_readlane_b32 s0, v246, 0
	v_readlane_b32 s1, v246, 1
	s_and_b64 vcc, exec, s[0:1]
	s_cbranch_vccz .LBB0_586
	s_cmp_lt_i32 s96, 7
	s_cbranch_scc1 .LBB0_588
	s_cmp_lg_u32 s96, 0x63
	s_cselect_b64 s[6:7], -1, 0
	s_cbranch_execz .LBB0_589
	s_branch .LBB0_590

.LBB0_589:
	s_cmp_lg_u32 s96, 2
	s_cselect_b64 s[6:7], -1, 0
	s_cmp_eq_u32 s96, 6
	s_cselect_b64 s[6:7], 0, s[6:7]
